# XCD-local barriers now guarded at run time: each blockIdx&7 class must sit on one XCD (checked once via atomics), else all barriers stay global
# speedup vs baseline: 1.0093x; 1.0093x over previous
; #define LAS __attribute__((address_space(3)))
; __global__ void __launch_bounds__(256, 2) fwd_megakernel(Params p) {
;   __shared__ __attribute__((aligned(16))) char smem[SMEM_BYTES];
;   __shared__ uint4 xb_words;
;   __shared__ int s_tile;
;   char* ws = p.ws;
;   if (ws == nullptr) { cg::grid_group grid = cg::this_grid(); grid.sync(); }
;   if (threadIdx.x == 0) xb_words = make_uint4(0u, 0u, 0u, 0u);
;   __syncthreads();
;   const XcdBarrier xb = xcd_barrier_post((unsigned*)(ws + O_BAR), (volatile LAS unsigned*)&xb_words);
_Z14fwd_megakernel6Params:
	s_load_dwordx16 s[68:83], s[0:1], 0x80
	v_writelane_b32 v246, s2, 0
	s_mov_b64 s[2:3], 0
	s_waitcnt lgkmcnt(0)
	v_readlane_b32 s98, v246, 0
	s_and_b32 s98, s98, 7
	s_lshl_b32 s98, s98, 2
	s_getreg_b32 s99, hwreg(HW_REG_XCC_ID, 0, 4)
	v_mov_b32_e32 v2, s98
	v_add_u32_e32 v2, 0x13d8b900, v2
	s_add_u32 s98, s99, 1
	v_mov_b32_e32 v3, s98
	s_sub_u32 s99, 16, s99
	v_mov_b32_e32 v4, s99
	v_and_b32_e32 v5, 0x3ff, v0
	v_cmp_eq_u32_e32 vcc, 0, v5
	s_and_saveexec_b64 s[98:99], vcc
	global_atomic_umax v2, v3, s[82:83]
	global_atomic_umax v2, v4, s[82:83] offset:32
	s_mov_b64 exec, s[98:99]
	s_cmp_eq_u64 s[82:83], 0
	s_cbranch_scc1 .LBB0_2
	v_and_b32_e32 v216, 0x3ff, v0
	s_andn2_b64 vcc, exec, s[2:3]
	s_cbranch_vccz .LBB0_3
	s_branch .LBB0_14

; DI unsigned xb_add(unsigned* p, unsigned v) { return __hip_atomic_fetch_add(p, v, __ATOMIC_RELAXED, __HIP_MEMORY_SCOPE_AGENT); }
; DI void xcd_barrier(const XcdBarrier& b) {
;   asm volatile("s_waitcnt vmcnt(0)" ::: "memory");
;   __syncthreads();
;   if (threadIdx.x == 0) {
;     unsigned* bar = b.bar;
;     __builtin_amdgcn_s_waitcnt(0);
;     unsigned nloc = b.st[0], nx = b.st[1];
;     if (nloc == 0u) { xcd_barrier_complete(bar, b.x, nloc, nx); b.st[0] = nloc; b.st[1] = nx; }
;     const unsigned old = xb_add(&bar[XB_XSUB(b.x)], 1u);
;     const unsigned gen = old / nloc;
;     if (old + 1u == (gen + 1u) * nloc) {
.LBB0_272:
	s_cmp_lg_u32 s60, 0
	s_cbranch_scc1 .Llb_skipld
	v_lshlrev_b32_e32 v2, 2, v231
	v_add_u32_e32 v2, 0x13d8b900, v2
	global_load_dword v2, v2, s[82:83] sc1
	s_mov_b32 s32, 0
	s_waitcnt vmcnt(0)
	v_readlane_b32 s98, v2, 0
	v_readlane_b32 s99, v2, 8
	s_add_u32 s98, s98, s99
	s_cmp_lg_u32 s98, 17
	s_addc_u32 s32, s32, 0
	v_readlane_b32 s98, v2, 1
	v_readlane_b32 s99, v2, 9
	s_add_u32 s98, s98, s99
	s_cmp_lg_u32 s98, 17
	s_addc_u32 s32, s32, 0
	v_readlane_b32 s98, v2, 2
	v_readlane_b32 s99, v2, 10
	s_add_u32 s98, s98, s99
	s_cmp_lg_u32 s98, 17
	s_addc_u32 s32, s32, 0
	v_readlane_b32 s98, v2, 3
	v_readlane_b32 s99, v2, 11
	s_add_u32 s98, s98, s99
	s_cmp_lg_u32 s98, 17
	s_addc_u32 s32, s32, 0
	v_readlane_b32 s98, v2, 4
	v_readlane_b32 s99, v2, 12
	s_add_u32 s98, s98, s99
	s_cmp_lg_u32 s98, 17
	s_addc_u32 s32, s32, 0
	v_readlane_b32 s98, v2, 5
	v_readlane_b32 s99, v2, 13
	s_add_u32 s98, s98, s99
	s_cmp_lg_u32 s98, 17
	s_addc_u32 s32, s32, 0
	v_readlane_b32 s98, v2, 6
	v_readlane_b32 s99, v2, 14
	s_add_u32 s98, s98, s99
	s_cmp_lg_u32 s98, 17
	s_addc_u32 s32, s32, 0
	v_readlane_b32 s98, v2, 7
	v_readlane_b32 s99, v2, 15
	s_add_u32 s98, s98, s99
	s_cmp_lg_u32 s98, 17
	s_addc_u32 s32, s32, 0

; DI unsigned xb_ld(unsigned* p)              { return __hip_atomic_load(p, __ATOMIC_RELAXED, __HIP_MEMORY_SCOPE_AGENT); }
; DI unsigned xb_add(unsigned* p, unsigned v) { return __hip_atomic_fetch_add(p, v, __ATOMIC_RELAXED, __HIP_MEMORY_SCOPE_AGENT); }
; #define XB_SPIN(cond, bar) do { unsigned _sp = 0; while (cond) { __builtin_amdgcn_s_sleep(1); \
;     if ((++_sp & 255u) == 0u) { if (xb_ld(&(bar)[XB_TMO])) break; if (_sp > XB_SPIN_CAP) { atomicAdd(&(bar)[XB_TMO], 1u); break; } } } } while (0)
; DI void xcd_barrier(const XcdBarrier& b) {
;     ...
;     const unsigned old = xb_add(&bar[XB_XSUB(b.x)], 1u);
;     const unsigned gen = old / nloc;
;     if (old + 1u == (gen + 1u) * nloc) {
;       __builtin_amdgcn_fence(__ATOMIC_RELEASE, "agent");
;       asm volatile("s_waitcnt vmcnt(0)" ::: "memory");
;       const unsigned og = xb_add(&bar[XB_TOP], 1u);
;       const unsigned tg = og / nx;
;       if (og + 1u == (tg + 1u) * nx) xb_add(&bar[XB_TOPGEN], 1u);
;       else XB_SPIN(xb_ld(&bar[XB_TOPGEN]) == tg, bar);
;       __builtin_amdgcn_fence(__ATOMIC_ACQUIRE, "agent");
;       xb_add(&bar[XB_XGEN(b.x)], 1u);
;       asm volatile("s_waitcnt vmcnt(0)" ::: "memory");
.LBB0_307:
	s_andn2_saveexec_b64 s[26:27], s[26:27]
	s_cbranch_execz .LBB0_327
	s_mov_b64 s[26:27], exec
	buffer_wbl2 sc1
	s_waitcnt lgkmcnt(0)
	s_waitcnt vmcnt(0)
	s_cmp_eq_u32 s32, 0
	s_cbranch_scc1 .LBB0_324
	v_mbcnt_lo_u32_b32 v0, s26, 0
	v_mbcnt_hi_u32_b32 v0, s27, v0
	v_cmp_eq_u32_e32 vcc, 0, v0
	s_and_saveexec_b64 s[28:29], vcc
	s_cbranch_execz .LBB0_310
	s_bcnt1_i32_b64 s9, s[26:27]
	v_readlane_b32 s26, v244, 3
	v_mov_b32_e32 v3, s9
	v_readlane_b32 s27, v244, 4
	s_nop 4
	global_atomic_add v3, v1, v3, s[26:27] sc0

; DI unsigned xb_ld(unsigned* p)              { return __hip_atomic_load(p, __ATOMIC_RELAXED, __HIP_MEMORY_SCOPE_AGENT); }
; DI unsigned xb_add(unsigned* p, unsigned v) { return __hip_atomic_fetch_add(p, v, __ATOMIC_RELAXED, __HIP_MEMORY_SCOPE_AGENT); }
; #define XB_SPIN(cond, bar) do { unsigned _sp = 0; while (cond) { __builtin_amdgcn_s_sleep(1); \
;     if ((++_sp & 255u) == 0u) { if (xb_ld(&(bar)[XB_TMO])) break; if (_sp > XB_SPIN_CAP) { atomicAdd(&(bar)[XB_TMO], 1u); break; } } } } while (0)
; DI void xcd_barrier(const XcdBarrier& b) {
;     ...
;     const unsigned old = xb_add(&bar[XB_XSUB(b.x)], 1u);
;     const unsigned gen = old / nloc;
;     if (old + 1u == (gen + 1u) * nloc) {
;       __builtin_amdgcn_fence(__ATOMIC_RELEASE, "agent");
;       asm volatile("s_waitcnt vmcnt(0)" ::: "memory");
;       const unsigned og = xb_add(&bar[XB_TOP], 1u);
;       const unsigned tg = og / nx;
;       if (og + 1u == (tg + 1u) * nx) xb_add(&bar[XB_TOPGEN], 1u);
;       else XB_SPIN(xb_ld(&bar[XB_TOPGEN]) == tg, bar);
;       __builtin_amdgcn_fence(__ATOMIC_ACQUIRE, "agent");
;       xb_add(&bar[XB_XGEN(b.x)], 1u);
;       asm volatile("s_waitcnt vmcnt(0)" ::: "memory");
.LBB0_1160:
	s_andn2_saveexec_b64 s[24:25], s[24:25]
	s_cbranch_execz .LBB0_1180
	s_mov_b64 s[24:25], exec
	buffer_wbl2 sc1
	s_waitcnt lgkmcnt(0)
	s_waitcnt vmcnt(0)
	s_cmp_eq_u32 s32, 0
	s_cbranch_scc1 .LBB0_1177
	v_mbcnt_lo_u32_b32 v0, s24, 0
	v_mbcnt_hi_u32_b32 v0, s25, v0
	v_cmp_eq_u32_e32 vcc, 0, v0
	s_and_saveexec_b64 s[26:27], vcc
	s_cbranch_execz .LBB0_1163
	s_bcnt1_i32_b64 s9, s[24:25]
	v_readlane_b32 s24, v244, 3
	v_mov_b32_e32 v3, s9
	v_readlane_b32 s25, v244, 4
	s_nop 4
	global_atomic_add v3, v1, v3, s[24:25] sc0
